# ffn1/xq/ao k-loops: compiler's uncounted vmcnt(0) at the iteration head replaced by the template's counted vmcnt(8)
# speedup vs baseline: 1.0068x; 1.0068x over previous
.LBB0_37:
	s_add_u32 s4, s54, 0xfffc0080
	s_addc_u32 s5, s55, -1
	s_add_i32 s61, 0, 0x10000
	s_cmp_eq_u32 s60, 12
	s_cselect_b32 s57, s29, s5
	s_cselect_b32 s56, s33, s4
	v_add_u32_e32 v138, s61, v150
	s_cselect_b32 s5, s47, s59
	s_cselect_b32 s4, s49, s58
	s_add_i32 s64, 0, 0x14000
	ds_read_b128 v[152:155], v138
	ds_read_b128 v[156:159], v138 offset:1024
	ds_read_b128 v[160:163], v138 offset:2048
	ds_read_b128 v[164:167], v138 offset:3072
	v_add_u32_e32 v138, s64, v150
	s_waitcnt vmcnt(8)
	ds_read_b128 v[168:171], v138
	ds_read_b128 v[172:175], v138 offset:1024
	ds_read_b128 v[184:187], v138 offset:2048
	ds_read_b128 v[188:191], v138 offset:3072
	v_lshl_add_u64 v[138:139], s[54:55], 0, v[142:143]
	s_add_i32 m0, s3, 0xc000
	ds_read_b128 v[192:195], v151
	ds_read_b128 v[196:199], v151 offset:1024
	ds_read_b128 v[200:203], v151 offset:2048
	ds_read_b128 v[204:207], v151 offset:3072
	ds_read_b128 v[208:211], v151 offset:4096
	ds_read_b128 v[212:215], v151 offset:5120
	ds_read_b128 v[216:219], v151 offset:6144
	ds_read_b128 v[220:223], v151 offset:7168
	global_load_lds_dwordx4 v[138:139], off
	v_lshl_add_u64 v[138:139], s[54:55], 0, v[144:145]
	s_add_i32 m0, s3, 0xe000
	s_nop 0
	global_load_lds_dwordx4 v[138:139], off
	s_waitcnt vmcnt(8)
	s_waitcnt lgkmcnt(0)
	s_barrier
	s_setprio 1
	s_waitcnt lgkmcnt(0)
	v_mfma_f32_16x16x32_bf16 v[126:129], v[152:155], v[192:195], v[126:129]
	v_mfma_f32_16x16x32_bf16 v[122:125], v[160:163], v[192:195], v[122:125]
	v_mfma_f32_16x16x32_bf16 v[110:113], v[152:155], v[200:203], v[110:113]
	v_mfma_f32_16x16x32_bf16 v[106:109], v[160:163], v[200:203], v[106:109]
	v_mfma_f32_16x16x32_bf16 v[94:97], v[152:155], v[208:211], v[94:97]
	v_mfma_f32_16x16x32_bf16 v[90:93], v[160:163], v[208:211], v[90:93]
	v_mfma_f32_16x16x32_bf16 v[78:81], v[152:155], v[216:219], v[78:81]
	v_mfma_f32_16x16x32_bf16 v[74:77], v[160:163], v[216:219], v[74:77]
	v_mfma_f32_16x16x32_bf16 v[126:129], v[156:159], v[196:199], v[126:129]
	v_mfma_f32_16x16x32_bf16 v[122:125], v[164:167], v[196:199], v[122:125]
	v_mfma_f32_16x16x32_bf16 v[110:113], v[156:159], v[204:207], v[110:113]
	v_mfma_f32_16x16x32_bf16 v[106:109], v[164:167], v[204:207], v[106:109]
	v_mfma_f32_16x16x32_bf16 v[94:97], v[156:159], v[212:215], v[94:97]
	v_mfma_f32_16x16x32_bf16 v[90:93], v[164:167], v[212:215], v[90:93]
	v_mfma_f32_16x16x32_bf16 v[78:81], v[156:159], v[220:223], v[78:81]
	v_mfma_f32_16x16x32_bf16 v[74:77], v[164:167], v[220:223], v[74:77]
	s_setprio 0
	s_setprio 1
	v_mfma_f32_16x16x32_bf16 v[118:121], v[168:171], v[192:195], v[118:121]
	v_mfma_f32_16x16x32_bf16 v[114:117], v[184:187], v[192:195], v[114:117]
	v_mfma_f32_16x16x32_bf16 v[102:105], v[168:171], v[200:203], v[102:105]
	v_mfma_f32_16x16x32_bf16 v[98:101], v[184:187], v[200:203], v[98:101]
	v_mfma_f32_16x16x32_bf16 v[86:89], v[168:171], v[208:211], v[86:89]
	v_mfma_f32_16x16x32_bf16 v[82:85], v[184:187], v[208:211], v[82:85]
	v_mfma_f32_16x16x32_bf16 v[70:73], v[168:171], v[216:219], v[70:73]
	v_mfma_f32_16x16x32_bf16 v[66:69], v[184:187], v[216:219], v[66:69]
	v_mfma_f32_16x16x32_bf16 v[118:121], v[172:175], v[196:199], v[118:121]
	v_mfma_f32_16x16x32_bf16 v[114:117], v[188:191], v[196:199], v[114:117]
	v_mfma_f32_16x16x32_bf16 v[102:105], v[172:175], v[204:207], v[102:105]
	v_mfma_f32_16x16x32_bf16 v[98:101], v[188:191], v[204:207], v[98:101]
	v_mfma_f32_16x16x32_bf16 v[86:89], v[172:175], v[212:215], v[86:89]
	v_mfma_f32_16x16x32_bf16 v[82:85], v[188:191], v[212:215], v[82:85]
	v_mfma_f32_16x16x32_bf16 v[70:73], v[172:175], v[220:223], v[70:73]
	v_mfma_f32_16x16x32_bf16 v[66:69], v[188:191], v[220:223], v[66:69]
	s_setprio 0
	s_barrier
	s_add_i32 s61, s61, s2
	v_lshl_add_u64 v[138:139], s[4:5], 0, v[134:135]
	s_mov_b32 m0, s61
	ds_read_b128 v[192:195], v151 offset:16384
	ds_read_b128 v[196:199], v151 offset:17408
	ds_read_b128 v[200:203], v151 offset:18432
	ds_read_b128 v[204:207], v151 offset:19456
	ds_read_b128 v[208:211], v151 offset:20480
	ds_read_b128 v[212:215], v151 offset:21504
	ds_read_b128 v[216:219], v151 offset:22528
	ds_read_b128 v[220:223], v151 offset:23552
	global_load_lds_dwordx4 v[138:139], off
	s_add_i32 m0, s61, 0x2000
	s_add_u32 s62, s4, 0x40000
	v_lshl_add_u64 v[148:149], s[4:5], 0, v[130:131]
	s_addc_u32 s63, s5, 0
	s_add_i32 s61, s64, s2
	global_load_lds_dwordx4 v[148:149], off
	v_lshl_add_u64 v[182:183], s[62:63], 0, v[134:135]
	s_mov_b32 m0, s61
	v_lshl_add_u64 v[224:225], s[56:57], 0, v[132:133]
	global_load_lds_dwordx4 v[182:183], off
	v_lshl_add_u64 v[182:183], s[62:63], 0, v[130:131]
	s_add_i32 m0, s61, 0x2000
	s_nop 0
	global_load_lds_dwordx4 v[182:183], off
	v_lshl_add_u64 v[182:183], s[56:57], 0, v[136:137]
	s_mov_b32 m0, s3
	s_nop 0
	global_load_lds_dwordx4 v[182:183], off
	s_mov_b32 m0, s10
	s_nop 0
	global_load_lds_dwordx4 v[224:225], off
	s_waitcnt vmcnt(8)
	s_waitcnt lgkmcnt(0)
	s_barrier
	s_setprio 1
	s_waitcnt lgkmcnt(0)
	v_mfma_f32_16x16x32_bf16 v[60:63], v[152:155], v[192:195], v[60:63]
	v_mfma_f32_16x16x32_bf16 v[56:59], v[160:163], v[192:195], v[56:59]
	v_mfma_f32_16x16x32_bf16 v[44:47], v[152:155], v[200:203], v[44:47]
	v_mfma_f32_16x16x32_bf16 v[40:43], v[160:163], v[200:203], v[40:43]
	v_mfma_f32_16x16x32_bf16 v[28:31], v[152:155], v[208:211], v[28:31]
	v_mfma_f32_16x16x32_bf16 v[24:27], v[160:163], v[208:211], v[24:27]
	v_mfma_f32_16x16x32_bf16 v[12:15], v[152:155], v[216:219], v[12:15]
	v_mfma_f32_16x16x32_bf16 v[8:11], v[160:163], v[216:219], v[8:11]
	v_mfma_f32_16x16x32_bf16 v[60:63], v[156:159], v[196:199], v[60:63]
	v_mfma_f32_16x16x32_bf16 v[56:59], v[164:167], v[196:199], v[56:59]
	v_mfma_f32_16x16x32_bf16 v[44:47], v[156:159], v[204:207], v[44:47]
	v_mfma_f32_16x16x32_bf16 v[40:43], v[164:167], v[204:207], v[40:43]
	v_mfma_f32_16x16x32_bf16 v[28:31], v[156:159], v[212:215], v[28:31]
	v_mfma_f32_16x16x32_bf16 v[24:27], v[164:167], v[212:215], v[24:27]
	v_mfma_f32_16x16x32_bf16 v[12:15], v[156:159], v[220:223], v[12:15]
	v_mfma_f32_16x16x32_bf16 v[8:11], v[164:167], v[220:223], v[8:11]
	s_setprio 0
	s_setprio 1
	v_mfma_f32_16x16x32_bf16 v[52:55], v[168:171], v[192:195], v[52:55]
	v_mfma_f32_16x16x32_bf16 v[48:51], v[184:187], v[192:195], v[48:51]
	v_mfma_f32_16x16x32_bf16 v[36:39], v[168:171], v[200:203], v[36:39]
	v_mfma_f32_16x16x32_bf16 v[32:35], v[184:187], v[200:203], v[32:35]
	v_mfma_f32_16x16x32_bf16 v[20:23], v[168:171], v[208:211], v[20:23]
	v_mfma_f32_16x16x32_bf16 v[16:19], v[184:187], v[208:211], v[16:19]
	v_mfma_f32_16x16x32_bf16 v[4:7], v[168:171], v[216:219], v[4:7]
	v_mfma_f32_16x16x32_bf16 v[0:3], v[184:187], v[216:219], v[0:3]
	v_mfma_f32_16x16x32_bf16 v[52:55], v[172:175], v[196:199], v[52:55]
	v_mfma_f32_16x16x32_bf16 v[48:51], v[188:191], v[196:199], v[48:51]
	v_mfma_f32_16x16x32_bf16 v[36:39], v[172:175], v[204:207], v[36:39]
	v_mfma_f32_16x16x32_bf16 v[32:35], v[188:191], v[204:207], v[32:35]
	v_mfma_f32_16x16x32_bf16 v[20:23], v[172:175], v[212:215], v[20:23]
	v_mfma_f32_16x16x32_bf16 v[16:19], v[188:191], v[212:215], v[16:19]
	v_mfma_f32_16x16x32_bf16 v[4:7], v[172:175], v[220:223], v[4:7]
	v_mfma_f32_16x16x32_bf16 v[0:3], v[188:191], v[220:223], v[0:3]
	s_setprio 0
	s_barrier
	s_add_i32 s61, 0, 0x18000
	v_add_u32_e32 v147, s61, v150
	s_add_i32 s62, 0, 0x1c000
	ds_read_b128 v[152:155], v147
	ds_read_b128 v[156:159], v147 offset:1024
	ds_read_b128 v[160:163], v147 offset:2048
	ds_read_b128 v[164:167], v147 offset:3072
	v_add_u32_e32 v147, s62, v150
	ds_read_b128 v[168:171], v147
	ds_read_b128 v[172:175], v147 offset:1024
	ds_read_b128 v[184:187], v147 offset:2048
	ds_read_b128 v[188:191], v147 offset:3072
	s_add_u32 s56, s56, 0x40000
	s_addc_u32 s57, s57, 0
	s_mov_b32 m0, s18
	v_lshl_add_u64 v[226:227], s[56:57], 0, v[136:137]
	ds_read_b128 v[192:195], v151 offset:32768
	ds_read_b128 v[196:199], v151 offset:33792
	ds_read_b128 v[200:203], v151 offset:34816
	ds_read_b128 v[204:207], v151 offset:35840
	ds_read_b128 v[208:211], v151 offset:36864
	ds_read_b128 v[212:215], v151 offset:37888
	ds_read_b128 v[216:219], v151 offset:38912
	ds_read_b128 v[220:223], v151 offset:39936
	global_load_lds_dwordx4 v[226:227], off
	v_lshl_add_u64 v[226:227], s[56:57], 0, v[132:133]
	s_mov_b32 m0, s19
	s_nop 0
	global_load_lds_dwordx4 v[226:227], off
	s_waitcnt vmcnt(8)
	s_waitcnt lgkmcnt(0)
	s_barrier
	s_setprio 1
	s_waitcnt lgkmcnt(0)
	v_mfma_f32_16x16x32_bf16 v[126:129], v[152:155], v[192:195], v[126:129]
	v_mfma_f32_16x16x32_bf16 v[122:125], v[160:163], v[192:195], v[122:125]
	v_mfma_f32_16x16x32_bf16 v[110:113], v[152:155], v[200:203], v[110:113]
	v_mfma_f32_16x16x32_bf16 v[106:109], v[160:163], v[200:203], v[106:109]
	v_mfma_f32_16x16x32_bf16 v[94:97], v[152:155], v[208:211], v[94:97]
	v_mfma_f32_16x16x32_bf16 v[90:93], v[160:163], v[208:211], v[90:93]
	v_mfma_f32_16x16x32_bf16 v[78:81], v[152:155], v[216:219], v[78:81]
	v_mfma_f32_16x16x32_bf16 v[74:77], v[160:163], v[216:219], v[74:77]
	v_mfma_f32_16x16x32_bf16 v[126:129], v[156:159], v[196:199], v[126:129]
	v_mfma_f32_16x16x32_bf16 v[122:125], v[164:167], v[196:199], v[122:125]
	v_mfma_f32_16x16x32_bf16 v[110:113], v[156:159], v[204:207], v[110:113]
	v_mfma_f32_16x16x32_bf16 v[106:109], v[164:167], v[204:207], v[106:109]
	v_mfma_f32_16x16x32_bf16 v[94:97], v[156:159], v[212:215], v[94:97]
	v_mfma_f32_16x16x32_bf16 v[90:93], v[164:167], v[212:215], v[90:93]
	v_mfma_f32_16x16x32_bf16 v[78:81], v[156:159], v[220:223], v[78:81]
	v_mfma_f32_16x16x32_bf16 v[74:77], v[164:167], v[220:223], v[74:77]
	s_setprio 0
	s_setprio 1
	v_mfma_f32_16x16x32_bf16 v[118:121], v[168:171], v[192:195], v[118:121]
	v_mfma_f32_16x16x32_bf16 v[114:117], v[184:187], v[192:195], v[114:117]
	v_mfma_f32_16x16x32_bf16 v[102:105], v[168:171], v[200:203], v[102:105]
	v_mfma_f32_16x16x32_bf16 v[98:101], v[184:187], v[200:203], v[98:101]
	v_mfma_f32_16x16x32_bf16 v[86:89], v[168:171], v[208:211], v[86:89]
	v_mfma_f32_16x16x32_bf16 v[82:85], v[184:187], v[208:211], v[82:85]
	v_mfma_f32_16x16x32_bf16 v[70:73], v[168:171], v[216:219], v[70:73]
	v_mfma_f32_16x16x32_bf16 v[66:69], v[184:187], v[216:219], v[66:69]
	v_mfma_f32_16x16x32_bf16 v[118:121], v[172:175], v[196:199], v[118:121]
	v_mfma_f32_16x16x32_bf16 v[114:117], v[188:191], v[196:199], v[114:117]
	v_mfma_f32_16x16x32_bf16 v[102:105], v[172:175], v[204:207], v[102:105]
	v_mfma_f32_16x16x32_bf16 v[98:101], v[188:191], v[204:207], v[98:101]
	v_mfma_f32_16x16x32_bf16 v[86:89], v[172:175], v[212:215], v[86:89]
	v_mfma_f32_16x16x32_bf16 v[82:85], v[188:191], v[212:215], v[82:85]
	v_mfma_f32_16x16x32_bf16 v[70:73], v[172:175], v[220:223], v[70:73]
	v_mfma_f32_16x16x32_bf16 v[66:69], v[188:191], v[220:223], v[66:69]
	s_setprio 0
	s_barrier
	s_add_i32 s56, s61, s2
	v_lshl_add_u64 v[138:139], v[138:139], 0, s[14:15]
	s_mov_b32 m0, s56
	ds_read_b128 v[192:195], v151 offset:49152
	ds_read_b128 v[196:199], v151 offset:50176
	ds_read_b128 v[200:203], v151 offset:51200
	ds_read_b128 v[204:207], v151 offset:52224
	ds_read_b128 v[208:211], v151 offset:53248
	ds_read_b128 v[212:215], v151 offset:54272
	ds_read_b128 v[216:219], v151 offset:55296
	ds_read_b128 v[220:223], v151 offset:56320
	global_load_lds_dwordx4 v[138:139], off
	s_add_i32 m0, s56, 0x2000
	s_add_u32 s4, s4, 0x40080
	v_lshl_add_u64 v[138:139], v[148:149], 0, s[14:15]
	s_addc_u32 s5, s5, 0
	s_add_i32 s56, s62, s2
	global_load_lds_dwordx4 v[138:139], off
	v_lshl_add_u64 v[138:139], s[4:5], 0, v[134:135]
	s_mov_b32 m0, s56
	s_nop 0
	global_load_lds_dwordx4 v[138:139], off
	v_lshl_add_u64 v[138:139], s[4:5], 0, v[130:131]
	s_add_i32 m0, s56, 0x2000
	s_nop 0
	global_load_lds_dwordx4 v[138:139], off
	v_lshl_add_u64 v[138:139], v[182:183], 0, s[14:15]
	s_mov_b32 m0, s20
	s_nop 0
	global_load_lds_dwordx4 v[138:139], off
	v_lshl_add_u64 v[138:139], v[224:225], 0, s[14:15]
	s_mov_b32 m0, s21
	s_nop 0
	global_load_lds_dwordx4 v[138:139], off
	s_waitcnt vmcnt(8)
	s_waitcnt lgkmcnt(0)
	s_barrier
	s_setprio 1
	s_waitcnt lgkmcnt(0)
	v_mfma_f32_16x16x32_bf16 v[60:63], v[152:155], v[192:195], v[60:63]
	v_mfma_f32_16x16x32_bf16 v[56:59], v[160:163], v[192:195], v[56:59]
	v_mfma_f32_16x16x32_bf16 v[44:47], v[152:155], v[200:203], v[44:47]
	v_mfma_f32_16x16x32_bf16 v[40:43], v[160:163], v[200:203], v[40:43]
	v_mfma_f32_16x16x32_bf16 v[28:31], v[152:155], v[208:211], v[28:31]
	v_mfma_f32_16x16x32_bf16 v[24:27], v[160:163], v[208:211], v[24:27]
	v_mfma_f32_16x16x32_bf16 v[12:15], v[152:155], v[216:219], v[12:15]
	v_mfma_f32_16x16x32_bf16 v[8:11], v[160:163], v[216:219], v[8:11]
	v_mfma_f32_16x16x32_bf16 v[60:63], v[156:159], v[196:199], v[60:63]
	v_mfma_f32_16x16x32_bf16 v[56:59], v[164:167], v[196:199], v[56:59]
	v_mfma_f32_16x16x32_bf16 v[44:47], v[156:159], v[204:207], v[44:47]
	v_mfma_f32_16x16x32_bf16 v[40:43], v[164:167], v[204:207], v[40:43]
	v_mfma_f32_16x16x32_bf16 v[28:31], v[156:159], v[212:215], v[28:31]
	v_mfma_f32_16x16x32_bf16 v[24:27], v[164:167], v[212:215], v[24:27]
	v_mfma_f32_16x16x32_bf16 v[12:15], v[156:159], v[220:223], v[12:15]
	v_mfma_f32_16x16x32_bf16 v[8:11], v[164:167], v[220:223], v[8:11]
	s_setprio 0
	s_setprio 1
	v_mfma_f32_16x16x32_bf16 v[52:55], v[168:171], v[192:195], v[52:55]
	v_mfma_f32_16x16x32_bf16 v[48:51], v[184:187], v[192:195], v[48:51]
	v_mfma_f32_16x16x32_bf16 v[36:39], v[168:171], v[200:203], v[36:39]
	v_mfma_f32_16x16x32_bf16 v[32:35], v[184:187], v[200:203], v[32:35]
	v_mfma_f32_16x16x32_bf16 v[20:23], v[168:171], v[208:211], v[20:23]
	v_mfma_f32_16x16x32_bf16 v[16:19], v[184:187], v[208:211], v[16:19]
	v_mfma_f32_16x16x32_bf16 v[4:7], v[168:171], v[216:219], v[4:7]
	v_mfma_f32_16x16x32_bf16 v[0:3], v[184:187], v[216:219], v[0:3]
	v_mfma_f32_16x16x32_bf16 v[52:55], v[172:175], v[196:199], v[52:55]
	v_mfma_f32_16x16x32_bf16 v[48:51], v[188:191], v[196:199], v[48:51]
	v_mfma_f32_16x16x32_bf16 v[36:39], v[172:175], v[204:207], v[36:39]
	v_mfma_f32_16x16x32_bf16 v[32:35], v[188:191], v[204:207], v[32:35]
	v_mfma_f32_16x16x32_bf16 v[20:23], v[172:175], v[212:215], v[20:23]
	v_mfma_f32_16x16x32_bf16 v[16:19], v[188:191], v[212:215], v[16:19]
	v_mfma_f32_16x16x32_bf16 v[4:7], v[172:175], v[220:223], v[4:7]
	v_mfma_f32_16x16x32_bf16 v[0:3], v[188:191], v[220:223], v[0:3]
	s_setprio 0
	s_barrier
	s_add_i32 s60, s60, 2
	s_add_u32 s54, s54, 0x100
	s_addc_u32 s55, s55, 0
	s_add_u32 s58, s58, 0x100
	s_addc_u32 s59, s59, 0
	s_cmp_gt_u32 s60, 13
	s_cbranch_scc0 .LBB0_37
	s_and_b64 vcc, exec, s[40:41]
	s_cbranch_vccz .LBB0_40
	s_barrier

.LBB0_66:
	s_add_u32 s4, s36, 0xfffc0080
	s_addc_u32 s5, s37, -1
	s_add_i32 s28, 0, 0x10000
	s_cmp_eq_u32 s25, 12
	s_cselect_b32 s55, s10, s5
	s_cselect_b32 s54, s18, s4
	v_add_u32_e32 v138, s28, v152
	s_cselect_b32 s5, s19, s24
	s_cselect_b32 s4, s20, s21
	s_add_i32 s33, 0, 0x14000
	ds_read_b128 v[154:157], v138
	ds_read_b128 v[158:161], v138 offset:1024
	ds_read_b128 v[162:165], v138 offset:2048
	ds_read_b128 v[166:169], v138 offset:3072
	v_add_u32_e32 v138, s33, v152
	s_waitcnt vmcnt(8)
	ds_read_b128 v[170:173], v138
	ds_read_b128 v[186:189], v138 offset:1024
	ds_read_b128 v[190:193], v138 offset:2048
	ds_read_b128 v[194:197], v138 offset:3072
	v_lshl_add_u64 v[138:139], s[36:37], 0, v[142:143]
	s_add_i32 m0, s57, 0xc000
	ds_read_b128 v[198:201], v153
	ds_read_b128 v[202:205], v153 offset:1024
	ds_read_b128 v[206:209], v153 offset:2048
	ds_read_b128 v[210:213], v153 offset:3072
	ds_read_b128 v[214:217], v153 offset:4096
	ds_read_b128 v[218:221], v153 offset:5120
	ds_read_b128 v[222:225], v153 offset:6144
	ds_read_b128 v[226:229], v153 offset:7168
	global_load_lds_dwordx4 v[138:139], off
	v_lshl_add_u64 v[138:139], s[36:37], 0, v[144:145]
	s_add_i32 m0, s57, 0xe000
	s_nop 0
	global_load_lds_dwordx4 v[138:139], off
	s_waitcnt vmcnt(8)
	s_waitcnt lgkmcnt(0)
	s_barrier
	s_setprio 1
	s_waitcnt lgkmcnt(0)
	v_mfma_f32_16x16x32_bf16 v[126:129], v[154:157], v[198:201], v[126:129]
	v_mfma_f32_16x16x32_bf16 v[122:125], v[162:165], v[198:201], v[122:125]
	v_mfma_f32_16x16x32_bf16 v[110:113], v[154:157], v[206:209], v[110:113]
	v_mfma_f32_16x16x32_bf16 v[106:109], v[162:165], v[206:209], v[106:109]
	v_mfma_f32_16x16x32_bf16 v[94:97], v[154:157], v[214:217], v[94:97]
	v_mfma_f32_16x16x32_bf16 v[90:93], v[162:165], v[214:217], v[90:93]
	v_mfma_f32_16x16x32_bf16 v[78:81], v[154:157], v[222:225], v[78:81]
	v_mfma_f32_16x16x32_bf16 v[74:77], v[162:165], v[222:225], v[74:77]
	v_mfma_f32_16x16x32_bf16 v[126:129], v[158:161], v[202:205], v[126:129]
	v_mfma_f32_16x16x32_bf16 v[122:125], v[166:169], v[202:205], v[122:125]
	v_mfma_f32_16x16x32_bf16 v[110:113], v[158:161], v[210:213], v[110:113]
	v_mfma_f32_16x16x32_bf16 v[106:109], v[166:169], v[210:213], v[106:109]
	v_mfma_f32_16x16x32_bf16 v[94:97], v[158:161], v[218:221], v[94:97]
	v_mfma_f32_16x16x32_bf16 v[90:93], v[166:169], v[218:221], v[90:93]
	v_mfma_f32_16x16x32_bf16 v[78:81], v[158:161], v[226:229], v[78:81]
	v_mfma_f32_16x16x32_bf16 v[74:77], v[166:169], v[226:229], v[74:77]
	s_setprio 0
	s_setprio 1
	v_mfma_f32_16x16x32_bf16 v[118:121], v[170:173], v[198:201], v[118:121]
	v_mfma_f32_16x16x32_bf16 v[114:117], v[190:193], v[198:201], v[114:117]
	v_mfma_f32_16x16x32_bf16 v[102:105], v[170:173], v[206:209], v[102:105]
	v_mfma_f32_16x16x32_bf16 v[98:101], v[190:193], v[206:209], v[98:101]
	v_mfma_f32_16x16x32_bf16 v[86:89], v[170:173], v[214:217], v[86:89]
	v_mfma_f32_16x16x32_bf16 v[82:85], v[190:193], v[214:217], v[82:85]
	v_mfma_f32_16x16x32_bf16 v[70:73], v[170:173], v[222:225], v[70:73]
	v_mfma_f32_16x16x32_bf16 v[66:69], v[190:193], v[222:225], v[66:69]
	v_mfma_f32_16x16x32_bf16 v[118:121], v[186:189], v[202:205], v[118:121]
	v_mfma_f32_16x16x32_bf16 v[114:117], v[194:197], v[202:205], v[114:117]
	v_mfma_f32_16x16x32_bf16 v[102:105], v[186:189], v[210:213], v[102:105]
	v_mfma_f32_16x16x32_bf16 v[98:101], v[194:197], v[210:213], v[98:101]
	v_mfma_f32_16x16x32_bf16 v[86:89], v[186:189], v[218:221], v[86:89]
	v_mfma_f32_16x16x32_bf16 v[82:85], v[194:197], v[218:221], v[82:85]
	v_mfma_f32_16x16x32_bf16 v[70:73], v[186:189], v[226:229], v[70:73]
	v_mfma_f32_16x16x32_bf16 v[66:69], v[194:197], v[226:229], v[66:69]
	s_setprio 0
	s_barrier
	s_add_i32 s28, s28, s56
	v_lshl_add_u64 v[138:139], s[4:5], 0, v[134:135]
	s_mov_b32 m0, s28
	ds_read_b128 v[198:201], v153 offset:16384
	ds_read_b128 v[202:205], v153 offset:17408
	ds_read_b128 v[206:209], v153 offset:18432
	ds_read_b128 v[210:213], v153 offset:19456
	ds_read_b128 v[214:217], v153 offset:20480
	ds_read_b128 v[218:221], v153 offset:21504
	ds_read_b128 v[222:225], v153 offset:22528
	ds_read_b128 v[226:229], v153 offset:23552
	global_load_lds_dwordx4 v[138:139], off
	s_add_i32 m0, s28, 0x2000
	s_add_u32 s28, s4, 0x40000
	v_lshl_add_u64 v[148:149], s[4:5], 0, v[130:131]
	s_addc_u32 s29, s5, 0
	s_add_i32 s33, s33, s56
	global_load_lds_dwordx4 v[148:149], off
	v_lshl_add_u64 v[174:175], s[28:29], 0, v[134:135]
	s_mov_b32 m0, s33
	v_lshl_add_u64 v[182:183], s[54:55], 0, v[132:133]
	global_load_lds_dwordx4 v[174:175], off
	v_lshl_add_u64 v[174:175], s[28:29], 0, v[130:131]
	s_add_i32 m0, s33, 0x2000
	s_nop 0
	global_load_lds_dwordx4 v[174:175], off
	v_lshl_add_u64 v[174:175], s[54:55], 0, v[136:137]
	s_mov_b32 m0, s57
	s_nop 0
	global_load_lds_dwordx4 v[174:175], off
	s_mov_b32 m0, s58
	s_nop 0
	global_load_lds_dwordx4 v[182:183], off
	s_waitcnt vmcnt(8)
	s_waitcnt lgkmcnt(0)
	s_barrier
	s_setprio 1
	s_waitcnt lgkmcnt(0)
	v_mfma_f32_16x16x32_bf16 v[60:63], v[154:157], v[198:201], v[60:63]
	v_mfma_f32_16x16x32_bf16 v[56:59], v[162:165], v[198:201], v[56:59]
	v_mfma_f32_16x16x32_bf16 v[44:47], v[154:157], v[206:209], v[44:47]
	v_mfma_f32_16x16x32_bf16 v[40:43], v[162:165], v[206:209], v[40:43]
	v_mfma_f32_16x16x32_bf16 v[28:31], v[154:157], v[214:217], v[28:31]
	v_mfma_f32_16x16x32_bf16 v[24:27], v[162:165], v[214:217], v[24:27]
	v_mfma_f32_16x16x32_bf16 v[12:15], v[154:157], v[222:225], v[12:15]
	v_mfma_f32_16x16x32_bf16 v[8:11], v[162:165], v[222:225], v[8:11]
	v_mfma_f32_16x16x32_bf16 v[60:63], v[158:161], v[202:205], v[60:63]
	v_mfma_f32_16x16x32_bf16 v[56:59], v[166:169], v[202:205], v[56:59]
	v_mfma_f32_16x16x32_bf16 v[44:47], v[158:161], v[210:213], v[44:47]
	v_mfma_f32_16x16x32_bf16 v[40:43], v[166:169], v[210:213], v[40:43]
	v_mfma_f32_16x16x32_bf16 v[28:31], v[158:161], v[218:221], v[28:31]
	v_mfma_f32_16x16x32_bf16 v[24:27], v[166:169], v[218:221], v[24:27]
	v_mfma_f32_16x16x32_bf16 v[12:15], v[158:161], v[226:229], v[12:15]
	v_mfma_f32_16x16x32_bf16 v[8:11], v[166:169], v[226:229], v[8:11]
	s_setprio 0
	s_setprio 1
	v_mfma_f32_16x16x32_bf16 v[52:55], v[170:173], v[198:201], v[52:55]
	v_mfma_f32_16x16x32_bf16 v[48:51], v[190:193], v[198:201], v[48:51]
	v_mfma_f32_16x16x32_bf16 v[36:39], v[170:173], v[206:209], v[36:39]
	v_mfma_f32_16x16x32_bf16 v[32:35], v[190:193], v[206:209], v[32:35]
	v_mfma_f32_16x16x32_bf16 v[20:23], v[170:173], v[214:217], v[20:23]
	v_mfma_f32_16x16x32_bf16 v[16:19], v[190:193], v[214:217], v[16:19]
	v_mfma_f32_16x16x32_bf16 v[4:7], v[170:173], v[222:225], v[4:7]
	v_mfma_f32_16x16x32_bf16 v[0:3], v[190:193], v[222:225], v[0:3]
	v_mfma_f32_16x16x32_bf16 v[52:55], v[186:189], v[202:205], v[52:55]
	v_mfma_f32_16x16x32_bf16 v[48:51], v[194:197], v[202:205], v[48:51]
	v_mfma_f32_16x16x32_bf16 v[36:39], v[186:189], v[210:213], v[36:39]
	v_mfma_f32_16x16x32_bf16 v[32:35], v[194:197], v[210:213], v[32:35]
	v_mfma_f32_16x16x32_bf16 v[20:23], v[186:189], v[218:221], v[20:23]
	v_mfma_f32_16x16x32_bf16 v[16:19], v[194:197], v[218:221], v[16:19]
	v_mfma_f32_16x16x32_bf16 v[4:7], v[186:189], v[226:229], v[4:7]
	v_mfma_f32_16x16x32_bf16 v[0:3], v[194:197], v[226:229], v[0:3]
	s_setprio 0
	s_barrier
	s_add_i32 s33, 0, 0x18000
	v_add_u32_e32 v147, s33, v152
	s_add_i32 s47, 0, 0x1c000
	ds_read_b128 v[154:157], v147
	ds_read_b128 v[158:161], v147 offset:1024
	ds_read_b128 v[162:165], v147 offset:2048
	ds_read_b128 v[166:169], v147 offset:3072
	v_add_u32_e32 v147, s47, v152
	ds_read_b128 v[170:173], v147
	ds_read_b128 v[186:189], v147 offset:1024
	ds_read_b128 v[190:193], v147 offset:2048
	ds_read_b128 v[194:197], v147 offset:3072
	s_add_u32 s28, s54, 0x40000
	s_addc_u32 s29, s55, 0
	s_mov_b32 m0, s59
	v_lshl_add_u64 v[230:231], s[28:29], 0, v[136:137]
	ds_read_b128 v[198:201], v153 offset:32768
	ds_read_b128 v[202:205], v153 offset:33792
	ds_read_b128 v[206:209], v153 offset:34816
	ds_read_b128 v[210:213], v153 offset:35840
	ds_read_b128 v[214:217], v153 offset:36864
	ds_read_b128 v[218:221], v153 offset:37888
	ds_read_b128 v[222:225], v153 offset:38912
	ds_read_b128 v[226:229], v153 offset:39936
	global_load_lds_dwordx4 v[230:231], off
	v_lshl_add_u64 v[230:231], s[28:29], 0, v[132:133]
	s_mov_b32 m0, s60
	s_nop 0
	global_load_lds_dwordx4 v[230:231], off
	s_waitcnt vmcnt(8)
	s_waitcnt lgkmcnt(0)
	s_barrier
	s_setprio 1
	s_waitcnt lgkmcnt(0)
	v_mfma_f32_16x16x32_bf16 v[126:129], v[154:157], v[198:201], v[126:129]
	v_mfma_f32_16x16x32_bf16 v[122:125], v[162:165], v[198:201], v[122:125]
	v_mfma_f32_16x16x32_bf16 v[110:113], v[154:157], v[206:209], v[110:113]
	v_mfma_f32_16x16x32_bf16 v[106:109], v[162:165], v[206:209], v[106:109]
	v_mfma_f32_16x16x32_bf16 v[94:97], v[154:157], v[214:217], v[94:97]
	v_mfma_f32_16x16x32_bf16 v[90:93], v[162:165], v[214:217], v[90:93]
	v_mfma_f32_16x16x32_bf16 v[78:81], v[154:157], v[222:225], v[78:81]
	v_mfma_f32_16x16x32_bf16 v[74:77], v[162:165], v[222:225], v[74:77]
	v_mfma_f32_16x16x32_bf16 v[126:129], v[158:161], v[202:205], v[126:129]
	v_mfma_f32_16x16x32_bf16 v[122:125], v[166:169], v[202:205], v[122:125]
	v_mfma_f32_16x16x32_bf16 v[110:113], v[158:161], v[210:213], v[110:113]
	v_mfma_f32_16x16x32_bf16 v[106:109], v[166:169], v[210:213], v[106:109]
	v_mfma_f32_16x16x32_bf16 v[94:97], v[158:161], v[218:221], v[94:97]
	v_mfma_f32_16x16x32_bf16 v[90:93], v[166:169], v[218:221], v[90:93]
	v_mfma_f32_16x16x32_bf16 v[78:81], v[158:161], v[226:229], v[78:81]
	v_mfma_f32_16x16x32_bf16 v[74:77], v[166:169], v[226:229], v[74:77]
	s_setprio 0
	s_setprio 1
	v_mfma_f32_16x16x32_bf16 v[118:121], v[170:173], v[198:201], v[118:121]
	v_mfma_f32_16x16x32_bf16 v[114:117], v[190:193], v[198:201], v[114:117]
	v_mfma_f32_16x16x32_bf16 v[102:105], v[170:173], v[206:209], v[102:105]
	v_mfma_f32_16x16x32_bf16 v[98:101], v[190:193], v[206:209], v[98:101]
	v_mfma_f32_16x16x32_bf16 v[86:89], v[170:173], v[214:217], v[86:89]
	v_mfma_f32_16x16x32_bf16 v[82:85], v[190:193], v[214:217], v[82:85]
	v_mfma_f32_16x16x32_bf16 v[70:73], v[170:173], v[222:225], v[70:73]
	v_mfma_f32_16x16x32_bf16 v[66:69], v[190:193], v[222:225], v[66:69]
	v_mfma_f32_16x16x32_bf16 v[118:121], v[186:189], v[202:205], v[118:121]
	v_mfma_f32_16x16x32_bf16 v[114:117], v[194:197], v[202:205], v[114:117]
	v_mfma_f32_16x16x32_bf16 v[102:105], v[186:189], v[210:213], v[102:105]
	v_mfma_f32_16x16x32_bf16 v[98:101], v[194:197], v[210:213], v[98:101]
	v_mfma_f32_16x16x32_bf16 v[86:89], v[186:189], v[218:221], v[86:89]
	v_mfma_f32_16x16x32_bf16 v[82:85], v[194:197], v[218:221], v[82:85]
	v_mfma_f32_16x16x32_bf16 v[70:73], v[186:189], v[226:229], v[70:73]
	v_mfma_f32_16x16x32_bf16 v[66:69], v[194:197], v[226:229], v[66:69]
	s_setprio 0
	s_barrier
	s_add_i32 s28, s33, s56
	v_lshl_add_u64 v[138:139], v[138:139], 0, s[14:15]
	s_mov_b32 m0, s28
	ds_read_b128 v[198:201], v153 offset:49152
	ds_read_b128 v[202:205], v153 offset:50176
	ds_read_b128 v[206:209], v153 offset:51200
	ds_read_b128 v[210:213], v153 offset:52224
	ds_read_b128 v[214:217], v153 offset:53248
	ds_read_b128 v[218:221], v153 offset:54272
	ds_read_b128 v[222:225], v153 offset:55296
	ds_read_b128 v[226:229], v153 offset:56320
	global_load_lds_dwordx4 v[138:139], off
	s_add_i32 m0, s28, 0x2000
	s_add_u32 s4, s4, 0x40080
	v_lshl_add_u64 v[138:139], v[148:149], 0, s[14:15]
	s_addc_u32 s5, s5, 0
	s_add_i32 s28, s47, s56
	global_load_lds_dwordx4 v[138:139], off
	v_lshl_add_u64 v[138:139], s[4:5], 0, v[134:135]
	s_mov_b32 m0, s28
	s_nop 0
	global_load_lds_dwordx4 v[138:139], off
	v_lshl_add_u64 v[138:139], s[4:5], 0, v[130:131]
	s_add_i32 m0, s28, 0x2000
	s_nop 0
	global_load_lds_dwordx4 v[138:139], off
	v_lshl_add_u64 v[138:139], v[174:175], 0, s[14:15]
	s_mov_b32 m0, s61
	s_nop 0
	global_load_lds_dwordx4 v[138:139], off
	v_lshl_add_u64 v[138:139], v[182:183], 0, s[14:15]
	s_mov_b32 m0, s62
	s_nop 0
	global_load_lds_dwordx4 v[138:139], off
	s_waitcnt vmcnt(8)
	s_waitcnt lgkmcnt(0)
	s_barrier
	s_setprio 1
	s_waitcnt lgkmcnt(0)
	v_mfma_f32_16x16x32_bf16 v[60:63], v[154:157], v[198:201], v[60:63]
	v_mfma_f32_16x16x32_bf16 v[56:59], v[162:165], v[198:201], v[56:59]
	v_mfma_f32_16x16x32_bf16 v[44:47], v[154:157], v[206:209], v[44:47]
	v_mfma_f32_16x16x32_bf16 v[40:43], v[162:165], v[206:209], v[40:43]
	v_mfma_f32_16x16x32_bf16 v[28:31], v[154:157], v[214:217], v[28:31]
	v_mfma_f32_16x16x32_bf16 v[24:27], v[162:165], v[214:217], v[24:27]
	v_mfma_f32_16x16x32_bf16 v[12:15], v[154:157], v[222:225], v[12:15]
	v_mfma_f32_16x16x32_bf16 v[8:11], v[162:165], v[222:225], v[8:11]
	v_mfma_f32_16x16x32_bf16 v[60:63], v[158:161], v[202:205], v[60:63]
	v_mfma_f32_16x16x32_bf16 v[56:59], v[166:169], v[202:205], v[56:59]
	v_mfma_f32_16x16x32_bf16 v[44:47], v[158:161], v[210:213], v[44:47]
	v_mfma_f32_16x16x32_bf16 v[40:43], v[166:169], v[210:213], v[40:43]
	v_mfma_f32_16x16x32_bf16 v[28:31], v[158:161], v[218:221], v[28:31]
	v_mfma_f32_16x16x32_bf16 v[24:27], v[166:169], v[218:221], v[24:27]
	v_mfma_f32_16x16x32_bf16 v[12:15], v[158:161], v[226:229], v[12:15]
	v_mfma_f32_16x16x32_bf16 v[8:11], v[166:169], v[226:229], v[8:11]
	s_setprio 0
	s_setprio 1
	v_mfma_f32_16x16x32_bf16 v[52:55], v[170:173], v[198:201], v[52:55]
	v_mfma_f32_16x16x32_bf16 v[48:51], v[190:193], v[198:201], v[48:51]
	v_mfma_f32_16x16x32_bf16 v[36:39], v[170:173], v[206:209], v[36:39]
	v_mfma_f32_16x16x32_bf16 v[32:35], v[190:193], v[206:209], v[32:35]
	v_mfma_f32_16x16x32_bf16 v[20:23], v[170:173], v[214:217], v[20:23]
	v_mfma_f32_16x16x32_bf16 v[16:19], v[190:193], v[214:217], v[16:19]
	v_mfma_f32_16x16x32_bf16 v[4:7], v[170:173], v[222:225], v[4:7]
	v_mfma_f32_16x16x32_bf16 v[0:3], v[190:193], v[222:225], v[0:3]
	v_mfma_f32_16x16x32_bf16 v[52:55], v[186:189], v[202:205], v[52:55]
	v_mfma_f32_16x16x32_bf16 v[48:51], v[194:197], v[202:205], v[48:51]
	v_mfma_f32_16x16x32_bf16 v[36:39], v[186:189], v[210:213], v[36:39]
	v_mfma_f32_16x16x32_bf16 v[32:35], v[194:197], v[210:213], v[32:35]
	v_mfma_f32_16x16x32_bf16 v[20:23], v[186:189], v[218:221], v[20:23]
	v_mfma_f32_16x16x32_bf16 v[16:19], v[194:197], v[218:221], v[16:19]
	v_mfma_f32_16x16x32_bf16 v[4:7], v[186:189], v[226:229], v[4:7]
	v_mfma_f32_16x16x32_bf16 v[0:3], v[194:197], v[226:229], v[0:3]
	s_setprio 0
	s_barrier
	s_add_i32 s25, s25, 2
	s_add_u32 s36, s36, 0x100
	s_addc_u32 s37, s37, 0
	s_add_u32 s21, s21, 0x100
	s_addc_u32 s24, s24, 0
	s_cmp_gt_u32 s25, 13
	s_cbranch_scc0 .LBB0_66
	s_and_b64 vcc, exec, s[40:41]
	s_cbranch_vccz .LBB0_69
	s_barrier

.LBB0_244:
	s_add_u32 s4, s36, 0xfffe0080
	s_addc_u32 s5, s37, -1
	s_add_i32 s33, 0, 0x10000
	s_cmp_eq_u32 s29, 4
	s_cselect_b32 s51, s18, s5
	s_cselect_b32 s50, s19, s4
	v_add_u32_e32 v138, s33, v150
	s_cselect_b32 s5, s20, s25
	s_cselect_b32 s4, s21, s24
	s_add_i32 s43, 0, 0x14000
	ds_read_b128 v[146:149], v138
	ds_read_b128 v[154:157], v138 offset:1024
	ds_read_b128 v[158:161], v138 offset:2048
	ds_read_b128 v[162:165], v138 offset:3072
	v_add_u32_e32 v138, s43, v150
	ds_read_b128 v[166:169], v138
	s_waitcnt vmcnt(8)
	ds_read_b128 v[170:173], v138 offset:1024
	ds_read_b128 v[184:187], v138 offset:2048
	ds_read_b128 v[188:191], v138 offset:3072
	v_lshl_add_u64 v[174:175], s[36:37], 0, v[142:143]
	s_add_i32 m0, s53, 0xc000
	ds_read_b128 v[192:195], v152
	ds_read_b128 v[196:199], v152 offset:1024
	ds_read_b128 v[200:203], v152 offset:2048
	ds_read_b128 v[204:207], v152 offset:3072
	ds_read_b128 v[208:211], v152 offset:4096
	ds_read_b128 v[212:215], v152 offset:5120
	ds_read_b128 v[216:219], v152 offset:6144
	ds_read_b128 v[220:223], v152 offset:7168
	global_load_lds_dwordx4 v[174:175], off
	v_lshl_add_u64 v[174:175], s[36:37], 0, v[144:145]
	s_add_i32 m0, s53, 0xe000
	s_nop 0
	global_load_lds_dwordx4 v[174:175], off
	s_waitcnt vmcnt(8)
	s_waitcnt lgkmcnt(0)
	s_barrier
	s_setprio 1
	s_waitcnt lgkmcnt(0)
	v_mfma_f32_16x16x32_bf16 v[126:129], v[146:149], v[192:195], v[126:129]
	v_mfma_f32_16x16x32_bf16 v[122:125], v[158:161], v[192:195], v[122:125]
	v_mfma_f32_16x16x32_bf16 v[110:113], v[146:149], v[200:203], v[110:113]
	v_mfma_f32_16x16x32_bf16 v[106:109], v[158:161], v[200:203], v[106:109]
	v_mfma_f32_16x16x32_bf16 v[94:97], v[146:149], v[208:211], v[94:97]
	v_mfma_f32_16x16x32_bf16 v[90:93], v[158:161], v[208:211], v[90:93]
	v_mfma_f32_16x16x32_bf16 v[78:81], v[146:149], v[216:219], v[78:81]
	v_mfma_f32_16x16x32_bf16 v[74:77], v[158:161], v[216:219], v[74:77]
	v_mfma_f32_16x16x32_bf16 v[126:129], v[154:157], v[196:199], v[126:129]
	v_mfma_f32_16x16x32_bf16 v[122:125], v[162:165], v[196:199], v[122:125]
	v_mfma_f32_16x16x32_bf16 v[110:113], v[154:157], v[204:207], v[110:113]
	v_mfma_f32_16x16x32_bf16 v[106:109], v[162:165], v[204:207], v[106:109]
	v_mfma_f32_16x16x32_bf16 v[94:97], v[154:157], v[212:215], v[94:97]
	v_mfma_f32_16x16x32_bf16 v[90:93], v[162:165], v[212:215], v[90:93]
	v_mfma_f32_16x16x32_bf16 v[78:81], v[154:157], v[220:223], v[78:81]
	v_mfma_f32_16x16x32_bf16 v[74:77], v[162:165], v[220:223], v[74:77]
	s_setprio 0
	s_setprio 1
	v_mfma_f32_16x16x32_bf16 v[118:121], v[166:169], v[192:195], v[118:121]
	v_mfma_f32_16x16x32_bf16 v[114:117], v[184:187], v[192:195], v[114:117]
	v_mfma_f32_16x16x32_bf16 v[102:105], v[166:169], v[200:203], v[102:105]
	v_mfma_f32_16x16x32_bf16 v[98:101], v[184:187], v[200:203], v[98:101]
	v_mfma_f32_16x16x32_bf16 v[86:89], v[166:169], v[208:211], v[86:89]
	v_mfma_f32_16x16x32_bf16 v[82:85], v[184:187], v[208:211], v[82:85]
	v_mfma_f32_16x16x32_bf16 v[70:73], v[166:169], v[216:219], v[70:73]
	v_mfma_f32_16x16x32_bf16 v[66:69], v[184:187], v[216:219], v[66:69]
	v_mfma_f32_16x16x32_bf16 v[118:121], v[170:173], v[196:199], v[118:121]
	v_mfma_f32_16x16x32_bf16 v[114:117], v[188:191], v[196:199], v[114:117]
	v_mfma_f32_16x16x32_bf16 v[102:105], v[170:173], v[204:207], v[102:105]
	v_mfma_f32_16x16x32_bf16 v[98:101], v[188:191], v[204:207], v[98:101]
	v_mfma_f32_16x16x32_bf16 v[86:89], v[170:173], v[212:215], v[86:89]
	v_mfma_f32_16x16x32_bf16 v[82:85], v[188:191], v[212:215], v[82:85]
	v_mfma_f32_16x16x32_bf16 v[70:73], v[170:173], v[220:223], v[70:73]
	v_mfma_f32_16x16x32_bf16 v[66:69], v[188:191], v[220:223], v[66:69]
	s_setprio 0
	s_barrier
	s_add_i32 s33, s33, s52
	v_lshl_add_u64 v[174:175], s[4:5], 0, v[134:135]
	s_mov_b32 m0, s33
	ds_read_b128 v[192:195], v152 offset:16384
	ds_read_b128 v[196:199], v152 offset:17408
	ds_read_b128 v[200:203], v152 offset:18432
	ds_read_b128 v[204:207], v152 offset:19456
	ds_read_b128 v[208:211], v152 offset:20480
	ds_read_b128 v[212:215], v152 offset:21504
	ds_read_b128 v[216:219], v152 offset:22528
	ds_read_b128 v[220:223], v152 offset:23552
	global_load_lds_dwordx4 v[174:175], off
	s_add_i32 m0, s33, 0x2000
	s_add_u32 s58, s4, 0x20000
	v_lshl_add_u64 v[182:183], s[4:5], 0, v[130:131]
	s_addc_u32 s59, s5, 0
	s_add_i32 s33, s43, s52
	global_load_lds_dwordx4 v[182:183], off
	v_lshl_add_u64 v[224:225], s[58:59], 0, v[134:135]
	s_mov_b32 m0, s33
	v_lshl_add_u64 v[226:227], s[50:51], 0, v[132:133]
	global_load_lds_dwordx4 v[224:225], off
	v_lshl_add_u64 v[224:225], s[58:59], 0, v[130:131]
	s_add_i32 m0, s33, 0x2000
	s_nop 0
	global_load_lds_dwordx4 v[224:225], off
	v_lshl_add_u64 v[224:225], s[50:51], 0, v[136:137]
	s_mov_b32 m0, s53
	s_nop 0
	global_load_lds_dwordx4 v[224:225], off
	s_mov_b32 m0, s54
	s_nop 0
	global_load_lds_dwordx4 v[226:227], off
	s_waitcnt vmcnt(8)
	s_waitcnt lgkmcnt(0)
	s_barrier
	s_setprio 1
	s_waitcnt lgkmcnt(0)
	v_mfma_f32_16x16x32_bf16 v[60:63], v[146:149], v[192:195], v[60:63]
	v_mfma_f32_16x16x32_bf16 v[56:59], v[158:161], v[192:195], v[56:59]
	v_mfma_f32_16x16x32_bf16 v[44:47], v[146:149], v[200:203], v[44:47]
	v_mfma_f32_16x16x32_bf16 v[40:43], v[158:161], v[200:203], v[40:43]
	v_mfma_f32_16x16x32_bf16 v[28:31], v[146:149], v[208:211], v[28:31]
	v_mfma_f32_16x16x32_bf16 v[24:27], v[158:161], v[208:211], v[24:27]
	v_mfma_f32_16x16x32_bf16 v[12:15], v[146:149], v[216:219], v[12:15]
	v_mfma_f32_16x16x32_bf16 v[8:11], v[158:161], v[216:219], v[8:11]
	v_mfma_f32_16x16x32_bf16 v[60:63], v[154:157], v[196:199], v[60:63]
	v_mfma_f32_16x16x32_bf16 v[56:59], v[162:165], v[196:199], v[56:59]
	v_mfma_f32_16x16x32_bf16 v[44:47], v[154:157], v[204:207], v[44:47]
	v_mfma_f32_16x16x32_bf16 v[40:43], v[162:165], v[204:207], v[40:43]
	v_mfma_f32_16x16x32_bf16 v[28:31], v[154:157], v[212:215], v[28:31]
	v_mfma_f32_16x16x32_bf16 v[24:27], v[162:165], v[212:215], v[24:27]
	v_mfma_f32_16x16x32_bf16 v[12:15], v[154:157], v[220:223], v[12:15]
	v_mfma_f32_16x16x32_bf16 v[8:11], v[162:165], v[220:223], v[8:11]
	s_setprio 0
	s_setprio 1
	v_mfma_f32_16x16x32_bf16 v[52:55], v[166:169], v[192:195], v[52:55]
	v_mfma_f32_16x16x32_bf16 v[48:51], v[184:187], v[192:195], v[48:51]
	v_mfma_f32_16x16x32_bf16 v[36:39], v[166:169], v[200:203], v[36:39]
	v_mfma_f32_16x16x32_bf16 v[32:35], v[184:187], v[200:203], v[32:35]
	v_mfma_f32_16x16x32_bf16 v[20:23], v[166:169], v[208:211], v[20:23]
	v_mfma_f32_16x16x32_bf16 v[16:19], v[184:187], v[208:211], v[16:19]
	v_mfma_f32_16x16x32_bf16 v[4:7], v[166:169], v[216:219], v[4:7]
	v_mfma_f32_16x16x32_bf16 v[0:3], v[184:187], v[216:219], v[0:3]
	v_mfma_f32_16x16x32_bf16 v[52:55], v[170:173], v[196:199], v[52:55]
	v_mfma_f32_16x16x32_bf16 v[48:51], v[188:191], v[196:199], v[48:51]
	v_mfma_f32_16x16x32_bf16 v[36:39], v[170:173], v[204:207], v[36:39]
	v_mfma_f32_16x16x32_bf16 v[32:35], v[188:191], v[204:207], v[32:35]
	v_mfma_f32_16x16x32_bf16 v[20:23], v[170:173], v[212:215], v[20:23]
	v_mfma_f32_16x16x32_bf16 v[16:19], v[188:191], v[212:215], v[16:19]
	v_mfma_f32_16x16x32_bf16 v[4:7], v[170:173], v[220:223], v[4:7]
	v_mfma_f32_16x16x32_bf16 v[0:3], v[188:191], v[220:223], v[0:3]
	s_setprio 0
	s_barrier
	s_add_i32 s33, 0, 0x18000
	v_add_u32_e32 v138, s33, v150
	s_add_i32 s43, 0, 0x1c000
	ds_read_b128 v[146:149], v138
	ds_read_b128 v[154:157], v138 offset:1024
	ds_read_b128 v[158:161], v138 offset:2048
	ds_read_b128 v[162:165], v138 offset:3072
	v_add_u32_e32 v138, s43, v150
	ds_read_b128 v[166:169], v138
	ds_read_b128 v[170:173], v138 offset:1024
	ds_read_b128 v[184:187], v138 offset:2048
	ds_read_b128 v[188:191], v138 offset:3072
	s_add_u32 s50, s50, 0x20000
	s_addc_u32 s51, s51, 0
	s_mov_b32 m0, s55
	v_lshl_add_u64 v[228:229], s[50:51], 0, v[136:137]
	ds_read_b128 v[192:195], v152 offset:32768
	ds_read_b128 v[196:199], v152 offset:33792
	ds_read_b128 v[200:203], v152 offset:34816
	ds_read_b128 v[204:207], v152 offset:35840
	ds_read_b128 v[208:211], v152 offset:36864
	ds_read_b128 v[212:215], v152 offset:37888
	ds_read_b128 v[216:219], v152 offset:38912
	ds_read_b128 v[220:223], v152 offset:39936
	global_load_lds_dwordx4 v[228:229], off
	v_lshl_add_u64 v[228:229], s[50:51], 0, v[132:133]
	s_mov_b32 m0, s56
	s_nop 0
	global_load_lds_dwordx4 v[228:229], off
	s_waitcnt vmcnt(8)
	s_waitcnt lgkmcnt(0)
	s_barrier
	s_setprio 1
	s_waitcnt lgkmcnt(0)
	v_mfma_f32_16x16x32_bf16 v[126:129], v[146:149], v[192:195], v[126:129]
	v_mfma_f32_16x16x32_bf16 v[122:125], v[158:161], v[192:195], v[122:125]
	v_mfma_f32_16x16x32_bf16 v[110:113], v[146:149], v[200:203], v[110:113]
	v_mfma_f32_16x16x32_bf16 v[106:109], v[158:161], v[200:203], v[106:109]
	v_mfma_f32_16x16x32_bf16 v[94:97], v[146:149], v[208:211], v[94:97]
	v_mfma_f32_16x16x32_bf16 v[90:93], v[158:161], v[208:211], v[90:93]
	v_mfma_f32_16x16x32_bf16 v[78:81], v[146:149], v[216:219], v[78:81]
	v_mfma_f32_16x16x32_bf16 v[74:77], v[158:161], v[216:219], v[74:77]
	v_mfma_f32_16x16x32_bf16 v[126:129], v[154:157], v[196:199], v[126:129]
	v_mfma_f32_16x16x32_bf16 v[122:125], v[162:165], v[196:199], v[122:125]
	v_mfma_f32_16x16x32_bf16 v[110:113], v[154:157], v[204:207], v[110:113]
	v_mfma_f32_16x16x32_bf16 v[106:109], v[162:165], v[204:207], v[106:109]
	v_mfma_f32_16x16x32_bf16 v[94:97], v[154:157], v[212:215], v[94:97]
	v_mfma_f32_16x16x32_bf16 v[90:93], v[162:165], v[212:215], v[90:93]
	v_mfma_f32_16x16x32_bf16 v[78:81], v[154:157], v[220:223], v[78:81]
	v_mfma_f32_16x16x32_bf16 v[74:77], v[162:165], v[220:223], v[74:77]
	s_setprio 0
	s_setprio 1
	v_mfma_f32_16x16x32_bf16 v[118:121], v[166:169], v[192:195], v[118:121]
	v_mfma_f32_16x16x32_bf16 v[114:117], v[184:187], v[192:195], v[114:117]
	v_mfma_f32_16x16x32_bf16 v[102:105], v[166:169], v[200:203], v[102:105]
	v_mfma_f32_16x16x32_bf16 v[98:101], v[184:187], v[200:203], v[98:101]
	v_mfma_f32_16x16x32_bf16 v[86:89], v[166:169], v[208:211], v[86:89]
	v_mfma_f32_16x16x32_bf16 v[82:85], v[184:187], v[208:211], v[82:85]
	v_mfma_f32_16x16x32_bf16 v[70:73], v[166:169], v[216:219], v[70:73]
	v_mfma_f32_16x16x32_bf16 v[66:69], v[184:187], v[216:219], v[66:69]
	v_mfma_f32_16x16x32_bf16 v[118:121], v[170:173], v[196:199], v[118:121]
	v_mfma_f32_16x16x32_bf16 v[114:117], v[188:191], v[196:199], v[114:117]
	v_mfma_f32_16x16x32_bf16 v[102:105], v[170:173], v[204:207], v[102:105]
	v_mfma_f32_16x16x32_bf16 v[98:101], v[188:191], v[204:207], v[98:101]
	v_mfma_f32_16x16x32_bf16 v[86:89], v[170:173], v[212:215], v[86:89]
	v_mfma_f32_16x16x32_bf16 v[82:85], v[188:191], v[212:215], v[82:85]
	v_mfma_f32_16x16x32_bf16 v[70:73], v[170:173], v[220:223], v[70:73]
	v_mfma_f32_16x16x32_bf16 v[66:69], v[188:191], v[220:223], v[66:69]
	s_setprio 0
	s_barrier
	s_add_i32 s33, s33, s52
	v_lshl_add_u64 v[174:175], v[174:175], 0, s[14:15]
	s_mov_b32 m0, s33
	ds_read_b128 v[192:195], v152 offset:49152
	ds_read_b128 v[196:199], v152 offset:50176
	ds_read_b128 v[200:203], v152 offset:51200
	ds_read_b128 v[204:207], v152 offset:52224
	ds_read_b128 v[208:211], v152 offset:53248
	ds_read_b128 v[212:215], v152 offset:54272
	ds_read_b128 v[216:219], v152 offset:55296
	ds_read_b128 v[220:223], v152 offset:56320
	global_load_lds_dwordx4 v[174:175], off
	s_add_i32 m0, s33, 0x2000
	s_add_u32 s4, s4, 0x20080
	v_lshl_add_u64 v[174:175], v[182:183], 0, s[14:15]
	s_addc_u32 s5, s5, 0
	s_add_i32 s33, s43, s52
	global_load_lds_dwordx4 v[174:175], off
	v_lshl_add_u64 v[174:175], s[4:5], 0, v[134:135]
	s_mov_b32 m0, s33
	s_nop 0
	global_load_lds_dwordx4 v[174:175], off
	v_lshl_add_u64 v[174:175], s[4:5], 0, v[130:131]
	s_add_i32 m0, s33, 0x2000
	s_nop 0
	global_load_lds_dwordx4 v[174:175], off
	v_lshl_add_u64 v[174:175], v[224:225], 0, s[14:15]
	s_mov_b32 m0, s28
	s_nop 0
	global_load_lds_dwordx4 v[174:175], off
	v_lshl_add_u64 v[174:175], v[226:227], 0, s[14:15]
	s_mov_b32 m0, s57
	s_nop 0
	global_load_lds_dwordx4 v[174:175], off
	s_waitcnt vmcnt(8)
	s_waitcnt lgkmcnt(0)
	s_barrier
	s_setprio 1
	s_waitcnt lgkmcnt(0)
	v_mfma_f32_16x16x32_bf16 v[60:63], v[146:149], v[192:195], v[60:63]
	v_mfma_f32_16x16x32_bf16 v[56:59], v[158:161], v[192:195], v[56:59]
	v_mfma_f32_16x16x32_bf16 v[44:47], v[146:149], v[200:203], v[44:47]
	v_mfma_f32_16x16x32_bf16 v[40:43], v[158:161], v[200:203], v[40:43]
	v_mfma_f32_16x16x32_bf16 v[28:31], v[146:149], v[208:211], v[28:31]
	v_mfma_f32_16x16x32_bf16 v[24:27], v[158:161], v[208:211], v[24:27]
	v_mfma_f32_16x16x32_bf16 v[12:15], v[146:149], v[216:219], v[12:15]
	v_mfma_f32_16x16x32_bf16 v[8:11], v[158:161], v[216:219], v[8:11]
	v_mfma_f32_16x16x32_bf16 v[60:63], v[154:157], v[196:199], v[60:63]
	v_mfma_f32_16x16x32_bf16 v[56:59], v[162:165], v[196:199], v[56:59]
	v_mfma_f32_16x16x32_bf16 v[44:47], v[154:157], v[204:207], v[44:47]
	v_mfma_f32_16x16x32_bf16 v[40:43], v[162:165], v[204:207], v[40:43]
	v_mfma_f32_16x16x32_bf16 v[28:31], v[154:157], v[212:215], v[28:31]
	v_mfma_f32_16x16x32_bf16 v[24:27], v[162:165], v[212:215], v[24:27]
	v_mfma_f32_16x16x32_bf16 v[12:15], v[154:157], v[220:223], v[12:15]
	v_mfma_f32_16x16x32_bf16 v[8:11], v[162:165], v[220:223], v[8:11]
	s_setprio 0
	s_setprio 1
	v_mfma_f32_16x16x32_bf16 v[52:55], v[166:169], v[192:195], v[52:55]
	v_mfma_f32_16x16x32_bf16 v[48:51], v[184:187], v[192:195], v[48:51]
	v_mfma_f32_16x16x32_bf16 v[36:39], v[166:169], v[200:203], v[36:39]
	v_mfma_f32_16x16x32_bf16 v[32:35], v[184:187], v[200:203], v[32:35]
	v_mfma_f32_16x16x32_bf16 v[20:23], v[166:169], v[208:211], v[20:23]
	v_mfma_f32_16x16x32_bf16 v[16:19], v[184:187], v[208:211], v[16:19]
	v_mfma_f32_16x16x32_bf16 v[4:7], v[166:169], v[216:219], v[4:7]
	v_mfma_f32_16x16x32_bf16 v[0:3], v[184:187], v[216:219], v[0:3]
	v_mfma_f32_16x16x32_bf16 v[52:55], v[170:173], v[196:199], v[52:55]
	v_mfma_f32_16x16x32_bf16 v[48:51], v[188:191], v[196:199], v[48:51]
	v_mfma_f32_16x16x32_bf16 v[36:39], v[170:173], v[204:207], v[36:39]
	v_mfma_f32_16x16x32_bf16 v[32:35], v[188:191], v[204:207], v[32:35]
	v_mfma_f32_16x16x32_bf16 v[20:23], v[170:173], v[212:215], v[20:23]
	v_mfma_f32_16x16x32_bf16 v[16:19], v[188:191], v[212:215], v[16:19]
	v_mfma_f32_16x16x32_bf16 v[4:7], v[170:173], v[220:223], v[4:7]
	v_mfma_f32_16x16x32_bf16 v[0:3], v[188:191], v[220:223], v[0:3]
	s_setprio 0
	s_barrier
	s_add_i32 s29, s29, 2
	s_add_u32 s36, s36, 0x100
	s_addc_u32 s37, s37, 0
	s_add_u32 s24, s24, 0x100
	s_addc_u32 s25, s25, 0
	s_cmp_gt_u32 s29, 5
	s_cbranch_scc0 .LBB0_244
	s_and_b64 vcc, exec, s[40:41]
	s_cbranch_vccz .LBB0_247
	s_barrier
